# strategy 9 (loop-edge): MLA loop head shortened - next tile's K/V fragment LDS read addresses precomputed in the hazard gap, reads issue right after the barrier
# baseline (speedup 1.0000x reference)
; DI int get_tid() { int t = threadIdx.x; asm volatile("" : "+v"(t)); return t; }
; template <int DK, int MODE> ...
;     ...
;   const int tid = get_tid(), lane = tid & 63, wave = __builtin_amdgcn_readfirstlane(tid >> 6), l32 = lane & 31, h = lane >> 5;
;   const int tq0 = qb * 128 + 32 * wave;
;   const int qpos = tq0 + l32;
;   bf16x8 qf[NKS];
;   {
;     const bf16_t* qp = Q + (size_t)qpos * DK + h * 8;
; #pragma unroll
;     for (int ks = 0; ks < NKS; ++ks) qf[ks] = *(const bf16x8*)(qp + ks * 16);
; #pragma unroll
;     for (int ks = 0; ks < NKS; ++ks) asm volatile("" : "+v"(qf[ks]));
;   }
;   float Fref = 0.f;
;   if (MODE == 1) Fref = F[qb * 128];
;   f32x16 o0, o1;
; #pragma unroll
;   for (int e = 0; e < 16; ++e) { o0[e] = 0.f; o1[e] = 0.f; }
;   float m = -1e30f, lsum = 0.f, R = 1.f;
;   u32x4 rk[NKL], rv[2];
;   float rf = 0.f;
;   auto gload = [&](int jt) {
; #pragma unroll
;     for (int i = 0; i < NKL; ++i) {
;       const int id = tid + 256 * i, row = id / KCH, ch = id % KCH;
;       rk[i] = *(const u32x4*)(K + (size_t)(jt * 64 + row) * DK + ch * 8);
;     }
; #pragma unroll
;     for (int i = 0; i < 2; ++i) {
;       const int id = tid + 256 * i, row = id >> 3, ch = id & 7;
;       rv[i] = *(const u32x4*)(Vt + (size_t)row * Skv + jt * 64 + ch * 8);
;     }
;     if (MODE == 1) rf = F[jt * 64 + (tid & 63)];
;   };
;     ...
;   gload(ASC ? start : ntiles - 1);
;   swrite(0);
;   __syncthreads();
.LBB0_522:
	s_and_b64 s[0:1], s[56:57], exec
	s_cselect_b32 s0, s63, s64
	s_and_b64 vcc, exec, s[48:49]
	s_mov_b64 s[4:5], -1
	s_cbranch_vccz .LBB0_541
	s_load_dwordx2 s[20:21], s[18:19], 0x110
	s_load_dwordx4 s[8:11], s[18:19], 0x100
	v_mov_b32_e32 v36, v188
	s_load_dwordx4 s[4:7], s[18:19], 0x90
	v_mov_b32_e32 v161, v1
	s_waitcnt lgkmcnt(0)
	s_add_u32 s12, s8, s52
	s_addc_u32 s13, s9, s53
	s_add_u32 s22, s10, s52
	s_addc_u32 s23, s11, s53
	s_add_u32 s8, s20, s50
	v_readfirstlane_b32 s1, v36
	s_addc_u32 s9, s21, s51
	s_ashr_i32 s1, s1, 1
	s_lshl_b32 s2, s0, 7
	s_andn2_b32 s1, s1, 31
	v_and_b32_e32 v37, 31, v36
	s_add_i32 s1, s1, s2
	v_bfe_u32 v38, v36, 5, 1
	v_or_b32_e32 v152, s1, v37
	s_waitcnt vmcnt(7)
	v_mov_b64_e32 v[2:3], s[12:13]
	v_mad_i64_i32 v[2:3], s[12:13], v152, s78, v[2:3]
	v_lshlrev_b32_e32 v0, 4, v38
	v_lshl_add_u64 v[2:3], v[2:3], 0, v[0:1]
	global_load_dwordx4 v[80:83], v[2:3], off
	global_load_dwordx4 v[128:131], v[2:3], off offset:32
	global_load_dwordx4 v[124:127], v[2:3], off offset:64
	global_load_dwordx4 v[120:123], v[2:3], off offset:96
	global_load_dwordx4 v[116:119], v[2:3], off offset:128
	global_load_dwordx4 v[112:115], v[2:3], off offset:160
	v_mul_hi_i32 v2, v36, s69
	v_lshrrev_b32_e32 v3, 31, v2
	v_ashrrev_i32_e32 v2, 1, v2
	s_waitcnt vmcnt(7)
	v_add_u32_e32 v28, 0x100, v36
	v_add_u32_e32 v39, v2, v3
	v_mul_hi_i32 v6, v28, s69
	v_mul_lo_u32 v2, v39, 12
	v_lshrrev_b32_e32 v7, 31, v6
	v_ashrrev_i32_e32 v6, 1, v6
	v_add_u32_e32 v12, 0x200, v36
	v_sub_u32_e32 v40, v36, v2
	v_add_u32_e32 v41, v6, v7
	v_mul_hi_i32 v13, v12, s69
	v_lshlrev_b32_e32 v154, 3, v40
	v_mul_lo_u32 v6, v41, 12
	v_lshrrev_b32_e32 v18, 31, v13
	v_ashrrev_i32_e32 v13, 1, v13
	v_mov_b64_e32 v[10:11], s[22:23]
	v_ashrrev_i32_e32 v155, 31, v154
	v_sub_u32_e32 v42, v28, v6
	v_add_u32_e32 v43, v13, v18
	v_mad_i64_i32 v[2:3], s[12:13], v39, s78, v[10:11]
	v_lshlrev_b64 v[14:15], 1, v[154:155]
	v_lshlrev_b32_e32 v156, 3, v42
	v_mul_lo_u32 v13, v43, 12
	v_lshl_add_u64 v[2:3], v[2:3], 0, v[14:15]
	v_ashrrev_i32_e32 v157, 31, v156
	v_sub_u32_e32 v44, v12, v13
	v_ashrrev_i32_e32 v22, 3, v36
	v_mad_i64_i32 v[6:7], s[12:13], v41, s78, v[10:11]
	v_lshlrev_b64 v[16:17], 1, v[156:157]
	v_lshlrev_b32_e32 v158, 3, v44
	v_ashrrev_i32_e32 v23, 31, v22
	v_lshl_add_u64 v[6:7], v[6:7], 0, v[16:17]
	v_ashrrev_i32_e32 v159, 31, v158
	v_lshlrev_b64 v[20:21], 14, v[22:23]
	v_lshlrev_b32_e32 v23, 3, v36
	s_waitcnt vmcnt(6)
	v_ashrrev_i32_e32 v32, 3, v28
	v_mad_i64_i32 v[10:11], s[12:13], v43, s78, v[10:11]
	v_lshlrev_b64 v[18:19], 1, v[158:159]
	v_and_b32_e32 v23, 56, v23
	v_ashrrev_i32_e32 v33, 31, v32
	v_lshl_add_u64 v[10:11], v[10:11], 0, v[18:19]
	v_lshl_add_u64 v[24:25], s[8:9], 0, v[20:21]
	v_lshlrev_b32_e32 v160, 1, v23
	v_lshlrev_b64 v[34:35], 14, v[32:33]
	v_lshl_add_u64 v[24:25], v[24:25], 0, v[160:161]
	v_lshl_add_u64 v[28:29], s[8:9], 0, v[34:35]
	v_lshl_add_u64 v[28:29], v[28:29], 0, v[160:161]
	v_mul_lo_u32 v159, v39, s70
	v_lshlrev_b32_e32 v23, 4, v40
	v_lshl_add_u32 v23, v159, 1, v23
	v_mul_lo_u32 v161, v41, s70
	s_or_b32 s8, s1, 31
	s_movk_i32 s9, 0xd0
	s_or_b32 s2, s2, 64
	v_mad_u32_u24 v175, v37, s9, v0
	s_add_u32 s9, s20, s44
	v_mul_lo_u32 v172, v43, s70
	v_lshlrev_b32_e32 v0, 6, v37
	s_addc_u32 s13, s21, s45
	v_mul_lo_u32 v173, v22, s33
	v_sub_u32_e32 v157, v175, v0
	global_load_dwordx4 v[2:5], v[2:3], off
	s_add_u32 s12, s9, 0x80
	global_load_dwordx4 v[6:9], v[6:7], off
	v_lshlrev_b32_e32 v0, 4, v36
	global_load_dwordx4 v[10:13], v[10:11], off
	v_mul_lo_u32 v174, v32, s33
	global_load_dwordx4 v[24:27], v[24:25], off
	s_addc_u32 s13, s13, 0
	global_load_dwordx4 v[28:31], v[28:29], off
	v_and_b32_e32 v0, 0x70, v0
	v_or_b32_e32 v34, v34, v0
	v_or_b32_e32 v20, v20, v0
	s_add_u32 s10, s10, 0x3000
	v_lshl_add_u64 v[162:163], s[12:13], 0, v[34:35]
	v_lshl_add_u64 v[164:165], s[12:13], 0, v[20:21]
	s_addc_u32 s11, s11, 0
	v_lshlrev_b32_e32 v149, 2, v38
	v_mov_b32_e32 v0, v1
	v_ashrrev_i32_e32 v153, 31, v152
	s_mov_b32 s9, 0
	v_mov_b32_e32 v155, 0xf149f2ca
	v_mov_b32_e32 v151, 0
	s_waitcnt vmcnt(4)
	ds_write_b128 v23, v[2:5]
	v_lshlrev_b32_e32 v2, 4, v42
	v_lshl_add_u32 v2, v161, 1, v2
	s_waitcnt vmcnt(3)
	ds_write_b128 v2, v[6:9]
	v_lshlrev_b32_e32 v2, 4, v44
	v_lshl_add_u32 v2, v172, 1, v2
	s_waitcnt vmcnt(2)
	ds_write_b128 v2, v[10:13]
	v_lshl_add_u32 v2, v173, 1, v160
	s_waitcnt vmcnt(1)
	ds_write_b128 v2, v[24:27] offset:26624
	v_lshl_add_u32 v2, v174, 1, v160
	s_waitcnt vmcnt(0)
	ds_write_b128 v2, v[28:31] offset:26624
	v_mad_i64_i32 v[2:3], s[12:13], v43, s78, v[18:19]
	v_lshl_add_u64 v[166:167], s[10:11], 0, v[2:3]
	v_mad_i64_i32 v[2:3], s[12:13], v41, s78, v[16:17]
	v_lshl_add_u64 v[168:169], s[10:11], 0, v[2:3]
	v_mad_i64_i32 v[2:3], s[12:13], v39, s78, v[14:15]
	v_mov_b32_e32 v14, v1
	v_mov_b32_e32 v15, v1
	v_lshl_add_u64 v[170:171], s[10:11], 0, v[2:3]
	v_mov_b32_e32 v2, v1
	v_mov_b32_e32 v3, v1
	v_mov_b32_e32 v4, v1
	v_mov_b32_e32 v5, v1
	v_mov_b32_e32 v6, v1
	v_mov_b32_e32 v7, v1
	v_mov_b32_e32 v8, v1
	v_mov_b32_e32 v9, v1
	v_mov_b32_e32 v10, v1
	v_mov_b32_e32 v11, v1
	v_mov_b32_e32 v12, v1
	v_mov_b32_e32 v13, v1
	v_mov_b64_e32 v[30:31], v[14:15]
	v_mov_b64_e32 v[46:47], v[14:15]
	s_mov_b32 s10, 0
	v_mov_b64_e32 v[28:29], v[12:13]
	v_mov_b64_e32 v[26:27], v[10:11]
	v_mov_b64_e32 v[24:25], v[8:9]
	v_mov_b64_e32 v[22:23], v[6:7]
	v_mov_b64_e32 v[20:21], v[4:5]
	v_mov_b64_e32 v[18:19], v[2:3]
	v_mov_b64_e32 v[16:17], v[0:1]
	v_mov_b64_e32 v[44:45], v[12:13]
	v_mov_b64_e32 v[42:43], v[10:11]
	v_mov_b64_e32 v[40:41], v[8:9]
	v_mov_b64_e32 v[38:39], v[6:7]
	v_mov_b64_e32 v[36:37], v[4:5]
	v_mov_b64_e32 v[34:35], v[2:3]
	v_mov_b64_e32 v[32:33], v[0:1]
	s_waitcnt lgkmcnt(0)
	s_barrier
	v_lshlrev_b32_e32 v217, 1, v159
	v_lshl_add_u32 v217, v154, 1, v217
	v_lshlrev_b32_e32 v218, 1, v161
	v_lshl_add_u32 v218, v156, 1, v218
	v_lshlrev_b32_e32 v219, 1, v172
	v_lshl_add_u32 v219, v158, 1, v219
	v_lshl_add_u32 v220, v173, 1, v160
	v_lshl_add_u32 v221, v174, 1, v160
	v_lshl_add_u64 v[166:167], v[166:167], 0, s[46:47]
	v_lshl_add_u64 v[168:169], v[168:169], 0, s[46:47]
	v_lshl_add_u64 v[170:171], v[170:171], 0, s[46:47]
	v_mov_b32_e32 v240, v175
	v_mov_b32_e32 v239, v157
	s_branch .LBB0_526

; #define MFMA(a, b, c) __builtin_amdgcn_mfma_f32_32x32x16_bf16((a), (b), (c), 0, 0, 0)
; template <int DK, int MODE> ...
;     ...
;     const int jt = ASC ? start + it : ntiles - 1 - it;
;     const int cur = it & 1;
;     const bool more = it + 1 < nit;
;     if (more) gload(ASC ? jt + 1 : jt - 1);
;     const int key0 = jt * 64;
;     const bool active = !CAUSAL || (key0 <= tq0 + 31);
;     if (active) {
;       f32x16 s0, s1;
;       const bf16_t* kb = sK + cur * 64 * LDK + l32 * LDK + h * 8;
;       bf16x8 kf0[NKS], kf1[NKS];
; #pragma unroll
;       for (int ks = 0; ks < NKS; ++ks) { kf0[ks] = *(const bf16x8*)(kb + ks * 16); kf1[ks] = *(const bf16x8*)(kb + 32 * LDK + ks * 16); }
;       if (MODE == 1) {
;         const float* fb = sF + cur * 64 + 4 * h;
; #pragma unroll
;         for (int g = 0; g < 4; ++g) {
;           const f32x4 f0 = *(const f32x4*)(fb + 8 * g), f1 = *(const f32x4*)(fb + 32 + 8 * g);
;           s0[4 * g] = f0.x; s0[4 * g + 1] = f0.y; s0[4 * g + 2] = f0.z; s0[4 * g + 3] = f0.w;
;           s1[4 * g] = f1.x; s1[4 * g + 1] = f1.y; s1[4 * g + 2] = f1.z; s1[4 * g + 3] = f1.w;
;         }
;       } else {
; #pragma unroll
;         for (int e = 0; e < 16; ++e) { s0[e] = 0.f; s1[e] = 0.f; }
;       }
;       __builtin_amdgcn_iglp_opt(0);
;       __builtin_amdgcn_s_setprio(1);
; #pragma unroll
;       for (int ks = 0; ks < NKS; ++ks) { s0 = MFMA(kf0[ks], qf[ks], s0); s1 = MFMA(kf1[ks], qf[ks], s1); }
;       __builtin_amdgcn_s_setprio(0);
;       const bf16_t* vb = sV + cur * 64 * 72 + l32 * 72 + h * 8;
;       bf16x8 vf0[4], vf1[4];
; #pragma unroll
;       for (int j = 0; j < 4; ++j) { vf0[j] = *(const bf16x8*)(vb + j * 16); vf1[j] = *(const bf16x8*)(vb + 32 * 72 + j * 16); }
;       __builtin_amdgcn_sched_barrier(0);
;       const bool need_mask = CAUSAL && (key0 + 63 >= tq0);
;       bf16x8 pf[4];
;       if (MODE != 2) {
;         if (need_mask) {
; #pragma unroll
;           for (int e = 0; e < 16; ++e) {
;             const int key = key0 + 8 * (e >> 2) + 4 * h + (e & 3);
;             if (key > qpos) s0[e] = -1e30f;
;             if (key + 32 > qpos) s1[e] = -1e30f;
;           }
.LBB0_526:
	s_and_b32 s11, s10, 1
	s_cmp_gt_i32 s9, s8
	s_cbranch_scc1 .Lmla_inactive
	ds_read_b128 v[48:51], v240 offset:6656
	ds_read_b128 v[52:55], v240
	ds_read_b128 v[92:95], v240 offset:32
	ds_read_b128 v[96:99], v240 offset:6688
	ds_read_b128 v[100:103], v240 offset:64
	ds_read_b128 v[104:107], v240 offset:6720
	ds_read_b128 v[108:111], v240 offset:96
	ds_read_b128 v[132:135], v240 offset:6752
	ds_read_b128 v[136:139], v240 offset:128
	ds_read_b128 v[140:143], v240 offset:6784
	ds_read_b128 v[176:179], v240 offset:160
	ds_read_b128 v[180:183], v240 offset:6816
	s_setprio 1
	s_waitcnt lgkmcnt(10)
	v_mfma_f32_32x32x16_bf16 v[64:79], v[52:55], v[80:83], 0
	v_mfma_f32_32x32x16_bf16 v[48:63], v[48:51], v[80:83], 0
	global_load_dwordx4 v[88:91], v[170:171], off
	s_waitcnt lgkmcnt(9)
	v_mfma_f32_32x32x16_bf16 v[64:79], v[92:95], v[128:131], v[64:79]
	ds_read_b128 v[92:95], v239 offset:31328
	s_waitcnt lgkmcnt(9)
	v_mfma_f32_32x32x16_bf16 v[48:63], v[96:99], v[128:131], v[48:63]
	global_load_dwordx4 v[84:87], v[168:169], off
	ds_read_b128 v[96:99], v239 offset:26720
	s_waitcnt lgkmcnt(9)
	v_mfma_f32_32x32x16_bf16 v[64:79], v[100:103], v[124:127], v[64:79]
	ds_read_b128 v[100:103], v239 offset:26688
	s_waitcnt lgkmcnt(9)
	v_mfma_f32_32x32x16_bf16 v[48:63], v[104:107], v[124:127], v[48:63]
	global_load_dwordx4 v[10:13], v[166:167], off
	ds_read_b128 v[104:107], v239 offset:31296
	s_waitcnt lgkmcnt(9)
	v_mfma_f32_32x32x16_bf16 v[64:79], v[108:111], v[120:123], v[64:79]
	ds_read_b128 v[108:111], v239 offset:26656
	s_waitcnt lgkmcnt(9)
	v_mfma_f32_32x32x16_bf16 v[48:63], v[132:135], v[120:123], v[48:63]
	global_load_dwordx4 v[6:9], v[164:165], off
	ds_read_b128 v[132:135], v239 offset:31264
	s_waitcnt lgkmcnt(9)
	v_mfma_f32_32x32x16_bf16 v[64:79], v[136:139], v[116:119], v[64:79]
	ds_read_b128 v[136:139], v239 offset:26624
	s_waitcnt lgkmcnt(9)
	v_mfma_f32_32x32x16_bf16 v[48:63], v[140:143], v[116:119], v[48:63]
	s_nop 0
	global_load_dwordx4 v[2:5], v[162:163], off
	ds_read_b128 v[140:143], v239 offset:31232
	s_waitcnt lgkmcnt(9)
	v_mfma_f32_32x32x16_bf16 v[64:79], v[176:179], v[112:115], v[64:79]
	s_waitcnt lgkmcnt(8)
	v_mfma_f32_32x32x16_bf16 v[48:63], v[180:183], v[112:115], v[48:63]
	s_setprio 0
	s_add_i32 s12, s9, 63
	s_cmp_lt_i32 s12, s1
	s_cbranch_scc1 .LBB0_529
	v_add_u32_e32 v0, s9, v149
	v_add_u32_e32 v14, 32, v0
	v_cmp_le_i32_e32 vcc, v14, v152
	v_add_u32_e32 v14, 33, v0
	s_nop 4
	v_cndmask_b32_e32 v48, v198, v48, vcc
	v_cmp_lt_i32_e32 vcc, v0, v152
	s_nop 1
	v_cndmask_b32_e32 v65, v198, v65, vcc
	v_cmp_le_i32_e32 vcc, v0, v152
	s_nop 1
	v_cndmask_b32_e32 v64, v198, v64, vcc
	v_cmp_le_i32_e32 vcc, v14, v152
	v_add_u32_e32 v14, 2, v0
	s_nop 0
	v_cndmask_b32_e32 v49, v198, v49, vcc
	v_cmp_le_i32_e32 vcc, v14, v152
	v_add_u32_e32 v14, 34, v0
	s_nop 0
	v_cndmask_b32_e32 v66, v198, v66, vcc
	v_cmp_le_i32_e32 vcc, v14, v152
	v_add_u32_e32 v14, 3, v0
	s_nop 0
	v_cndmask_b32_e32 v50, v198, v50, vcc
	v_cmp_le_i32_e32 vcc, v14, v152
	v_add_u32_e32 v14, 35, v0
	s_nop 0
	v_cndmask_b32_e32 v67, v198, v67, vcc
	v_cmp_le_i32_e32 vcc, v14, v152
	v_add_u32_e32 v14, 8, v0
	s_nop 0
	v_cndmask_b32_e32 v51, v198, v51, vcc
	v_cmp_le_i32_e32 vcc, v14, v152
	v_add_u32_e32 v14, 40, v0
	s_nop 0
	v_cndmask_b32_e32 v68, v198, v68, vcc
	v_cmp_le_i32_e32 vcc, v14, v152
	v_add_u32_e32 v14, 9, v0
	s_nop 0
	v_cndmask_b32_e32 v52, v198, v52, vcc
	v_cmp_le_i32_e32 vcc, v14, v152
	v_add_u32_e32 v14, 41, v0
	s_nop 0
	v_cndmask_b32_e32 v69, v198, v69, vcc
	v_cmp_le_i32_e32 vcc, v14, v152
	v_add_u32_e32 v14, 10, v0
	s_nop 0
	v_cndmask_b32_e32 v53, v198, v53, vcc
	v_cmp_le_i32_e32 vcc, v14, v152
	v_add_u32_e32 v14, 42, v0
	s_nop 0
	v_cndmask_b32_e32 v70, v198, v70, vcc
	v_cmp_le_i32_e32 vcc, v14, v152
	v_add_u32_e32 v14, 11, v0
	s_nop 0
	v_cndmask_b32_e32 v54, v198, v54, vcc
	v_cmp_le_i32_e32 vcc, v14, v152
	v_add_u32_e32 v14, 43, v0
	s_nop 0
	v_cndmask_b32_e32 v71, v198, v71, vcc
	v_cmp_le_i32_e32 vcc, v14, v152
	v_add_u32_e32 v14, 16, v0
	s_nop 0
	v_cndmask_b32_e32 v55, v198, v55, vcc
	v_cmp_le_i32_e32 vcc, v14, v152
	v_add_u32_e32 v14, 48, v0
	s_nop 0
	v_cndmask_b32_e32 v72, v198, v72, vcc
	v_cmp_le_i32_e32 vcc, v14, v152
	v_add_u32_e32 v14, 17, v0
	s_nop 0
	v_cndmask_b32_e32 v56, v198, v56, vcc
	v_cmp_le_i32_e32 vcc, v14, v152
	v_add_u32_e32 v14, 49, v0
	s_nop 0
	v_cndmask_b32_e32 v73, v198, v73, vcc
	v_cmp_le_i32_e32 vcc, v14, v152
	v_add_u32_e32 v14, 18, v0
	s_nop 0
	v_cndmask_b32_e32 v57, v198, v57, vcc
	v_cmp_le_i32_e32 vcc, v14, v152
	v_add_u32_e32 v14, 50, v0
	s_nop 0
	v_cndmask_b32_e32 v74, v198, v74, vcc
	v_cmp_le_i32_e32 vcc, v14, v152
	v_add_u32_e32 v14, 19, v0
	s_nop 0
	v_cndmask_b32_e32 v58, v198, v58, vcc
	v_cmp_le_i32_e32 vcc, v14, v152
	v_add_u32_e32 v14, 51, v0
	s_nop 0
	v_cndmask_b32_e32 v75, v198, v75, vcc
	v_cmp_le_i32_e32 vcc, v14, v152
	v_add_u32_e32 v14, 24, v0
	s_nop 0
	v_cndmask_b32_e32 v59, v198, v59, vcc
	v_cmp_le_i32_e32 vcc, v14, v152
	v_add_u32_e32 v14, 56, v0
	s_nop 0
	v_cndmask_b32_e32 v76, v198, v76, vcc
	v_cmp_le_i32_e32 vcc, v14, v152
	v_add_u32_e32 v14, 25, v0
	s_nop 0
	v_cndmask_b32_e32 v60, v198, v60, vcc
	v_cmp_le_i32_e32 vcc, v14, v152
	v_add_u32_e32 v14, 57, v0
	s_nop 0
	v_cndmask_b32_e32 v77, v198, v77, vcc
	v_cmp_le_i32_e32 vcc, v14, v152
	v_add_u32_e32 v14, 26, v0
	s_nop 0
	v_cndmask_b32_e32 v61, v198, v61, vcc
	v_cmp_le_i32_e32 vcc, v14, v152
	v_add_u32_e32 v14, 58, v0
	s_nop 0
	v_cndmask_b32_e32 v78, v198, v78, vcc
	v_cmp_le_i32_e32 vcc, v14, v152
	v_add_u32_e32 v14, 27, v0
	v_add_u32_e32 v0, 59, v0
	v_cndmask_b32_e32 v62, v198, v62, vcc
	v_cmp_le_i32_e32 vcc, v14, v152
	s_nop 1
	v_cndmask_b32_e32 v79, v198, v79, vcc
	v_cmp_le_i32_e32 vcc, v0, v152
	s_nop 1
	v_cndmask_b32_e32 v63, v198, v63, vcc
; template <int DK, int MODE> ...
;     ...
;         float mx = s0[0];
; #pragma unroll
;         for (int e = 1; e < 16; ++e) mx = fmaxf(mx, s0[e]);
; #pragma unroll
;         for (int e = 0; e < 16; ++e) mx = fmaxf(mx, s1[e]);
;         mx = fmaxf(mx, __shfl_xor(mx, 32));
;         if (__any(mx > m + 8.f)) {
;           const float mnew = fmaxf(m, mx);
;           const float alpha = __builtin_amdgcn_exp2f(m - mnew);
;           m = mnew; lsum *= alpha;
; #pragma unroll
;           for (int e = 0; e < 16; ++e) { o0[e] *= alpha; o1[e] *= alpha; }
;         }
.LBB0_529:
	v_lshl_add_u64 v[162:163], v[162:163], 0, s[34:35]
	v_lshl_add_u64 v[164:165], v[164:165], 0, s[34:35]
	v_lshl_add_u64 v[166:167], v[166:167], 0, s[36:37]
	v_lshl_add_u64 v[168:169], v[168:169], 0, s[36:37]
	v_lshl_add_u64 v[170:171], v[170:171], 0, s[36:37]
	s_xor_b32 s100, s11, 1
	s_mul_i32 s101, s100, 0x3400
	s_lshl_b32 s100, s100, 12
	s_sub_i32 s100, s101, s100
	v_add_u32_e32 v241, s101, v217
	v_add_u32_e32 v242, s101, v218
	v_add_u32_e32 v243, s101, v219
	v_add_u32_e32 v244, s100, v220
	v_add_u32_e32 v245, s100, v221
	v_add_u32_e32 v240, s101, v175
	v_add_u32_e32 v239, s100, v157
	v_max_f32_e32 v0, v64, v65
	v_max3_f32 v0, v0, v66, v67
	v_max3_f32 v0, v0, v68, v69
	v_max3_f32 v0, v0, v70, v71
	v_max3_f32 v0, v0, v72, v73
	v_max3_f32 v0, v0, v74, v75
	v_max3_f32 v0, v0, v76, v77
	v_max3_f32 v0, v0, v78, v79
	v_max3_f32 v0, v0, v48, v49
	v_max3_f32 v0, v0, v50, v51
	v_max3_f32 v0, v0, v52, v53
	v_max3_f32 v0, v0, v54, v55
	v_max3_f32 v0, v0, v56, v57
	v_max3_f32 v0, v0, v58, v59
	v_max3_f32 v0, v0, v60, v61
	v_max3_f32 v0, v0, v62, v63
	ds_bpermute_b32 v14, v216, v0
	s_waitcnt lgkmcnt(0)
	v_max_f32_e32 v0, v0, v14
	v_add_f32_e32 v14, 0x41000000, v155
	v_cmp_gt_f32_e32 vcc, v0, v14
	s_cbranch_vccz .LBB0_524
	v_max_f32_e32 v0, v0, v0
	v_max_f32_e32 v14, v155, v155
	v_max_f32_e32 v14, v14, v0
	v_sub_f32_e32 v0, v155, v14
	v_exp_f32_e32 v0, v0
	v_mov_b32_e32 v155, v14
	v_pk_mul_f32 v[30:31], v[30:31], v[0:1] op_sel_hi:[1,0]
	v_pk_mul_f32 v[28:29], v[28:29], v[0:1] op_sel_hi:[1,0]
	v_pk_mul_f32 v[26:27], v[26:27], v[0:1] op_sel_hi:[1,0]
	v_pk_mul_f32 v[24:25], v[24:25], v[0:1] op_sel_hi:[1,0]
	v_pk_mul_f32 v[22:23], v[22:23], v[0:1] op_sel_hi:[1,0]
	v_pk_mul_f32 v[20:21], v[20:21], v[0:1] op_sel_hi:[1,0]
	v_pk_mul_f32 v[18:19], v[18:19], v[0:1] op_sel_hi:[1,0]
	v_pk_mul_f32 v[16:17], v[16:17], v[0:1] op_sel_hi:[1,0]
	v_pk_mul_f32 v[46:47], v[46:47], v[0:1] op_sel_hi:[1,0]
	v_pk_mul_f32 v[44:45], v[44:45], v[0:1] op_sel_hi:[1,0]
	v_pk_mul_f32 v[42:43], v[42:43], v[0:1] op_sel_hi:[1,0]
	v_pk_mul_f32 v[40:41], v[40:41], v[0:1] op_sel_hi:[1,0]
	v_pk_mul_f32 v[38:39], v[38:39], v[0:1] op_sel_hi:[1,0]
	v_pk_mul_f32 v[36:37], v[36:37], v[0:1] op_sel_hi:[1,0]
	v_pk_mul_f32 v[34:35], v[34:35], v[0:1] op_sel_hi:[1,0]
	v_pk_mul_f32 v[32:33], v[32:33], v[0:1] op_sel_hi:[1,0]
	v_mul_f32_e32 v151, v151, v0
	s_branch .LBB0_524
